# GRES epilogue: n0-n1 halves swapped between lane groups (DPP) so each 16B access covers 8 rows x 128B full lines
# speedup vs baseline: 1.0375x; 1.0220x over previous
;     __device__ __forceinline__ void operator()(const f32x4 (&acc)[2][2][4][2], const pg8::Unit& u, int wr, int wc, int fr, int fq) const {
;     ...
;         const int col0 = u.pn * 256 + wc * 32 + 4 * fq;
;         const float* gp = gate + (size_t)bidx * 6144 + col0;
;         f32x4 gv[2][2];
; #pragma unroll
;         for (int bj = 0; bj < 2; ++bj)
; #pragma unroll
;             for (int n = 0; n < 2; ++n) gv[bj][n] = *(const f32x4*)(gp + bj * 128 + n * 16);
; #pragma unroll
;         for (int ai = 0; ai < 2; ++ai)
; #pragma unroll
;             for (int m = 0; m < 4; ++m) { const size_t ro = (size_t)(wr * 64 + fr + ai * 128 + m * 16) * DM + col0;
; #pragma unroll
;                 for (int bj = 0; bj < 2; ++bj)
; #pragma unroll
;                     for (int n = 0; n < 2; ++n) { const size_t o = ro + bj * 128 + n * 16; *(f32x4*)(outp + o) = *(const f32x4*)(inp + o) + gv[bj][n] * acc[ai][bj][m][n]; } }
.LBB0_256:
	v_lshl_or_b32 v168, s70, 8, v171
	s_lshl_b64 s[22:23], s[24:25], 2
	v_ashrrev_i32_e32 v169, 31, v168
	s_add_u32 s22, s46, s22
	s_addc_u32 s23, s47, s23
	v_lshl_add_u64 v[130:131], v[168:169], 2, s[22:23]
	global_load_dwordx4 v[142:145], v[130:131], off
	global_load_dwordx4 v[138:141], v[130:131], off offset:64
	global_load_dwordx4 v[134:137], v[130:131], off offset:512
	s_nop 0
	global_load_dwordx4 v[130:133], v[130:131], off offset:576
	s_mov_b32 s70, s67
	s_mov_b32 s69, s68
	v_and_b32_e32 v173, 8, v220
	v_mul_i32_i24_e32 v173, 0xfffff008, v173
	v_cmp_eq_u32_e64 s[22:23], 0, v173
	v_add_lshl_u32 v176, v148, v168, 2
	v_add_lshl_u32 v177, v150, v168, 2
	v_add_lshl_u32 v178, v152, v168, 2
	v_add_lshl_u32 v179, v154, v168, 2
	v_add_lshl_u32 v180, v156, v168, 2
	v_add_lshl_u32 v181, v158, v168, 2
	v_add_lshl_u32 v182, v160, v168, 2
	v_add_lshl_u32 v183, v162, v168, 2
	v_add_u32_e32 v176, v176, v173
	v_add_u32_e32 v177, v177, v173
	v_add_u32_e32 v178, v178, v173
	v_add_u32_e32 v179, v179, v173
	v_add_u32_e32 v180, v180, v173
	v_add_u32_e32 v181, v181, v173
	v_add_u32_e32 v182, v182, v173
	v_add_u32_e32 v183, v183, v173
	v_add_u32_e32 v184, 0x8000, v176
	v_add_u32_e32 v185, 0x8000, v177
	v_add_u32_e32 v186, 0x8000, v178
	v_add_u32_e32 v187, 0x8000, v179
	v_add_u32_e32 v188, 0x8000, v180
	v_add_u32_e32 v189, 0x8000, v181
	v_add_u32_e32 v190, 0x8000, v182
	v_add_u32_e32 v191, 0x8000, v183
	global_load_dwordx4 v[192:195], v176, s[20:21]
	global_load_dwordx4 v[196:199], v184, s[20:21]
	global_load_dwordx4 v[200:203], v176, s[20:21] offset:512
	global_load_dwordx4 v[204:207], v184, s[20:21] offset:512
	global_load_dwordx4 v[208:211], v177, s[20:21]
	global_load_dwordx4 v[212:215], v185, s[20:21]
	global_load_dwordx4 v[216:219], v177, s[20:21] offset:512
	global_load_dwordx4 v[234:237], v185, s[20:21] offset:512
	global_load_dwordx4 v[238:241], v178, s[20:21]
	v_mov_b32_dpp v224, v126 row_ror:8 row_mask:0xf bank_mask:0x3
	v_mov_b32_dpp v225, v127 row_ror:8 row_mask:0xf bank_mask:0x3
	v_mov_b32_dpp v228, v128 row_ror:8 row_mask:0xf bank_mask:0x3
	v_mov_b32_dpp v229, v129 row_ror:8 row_mask:0xf bank_mask:0x3
	v_mov_b32_dpp v126, v122 row_ror:8 row_mask:0xf bank_mask:0xc
	v_mov_b32_dpp v127, v123 row_ror:8 row_mask:0xf bank_mask:0xc
	v_mov_b32_dpp v128, v124 row_ror:8 row_mask:0xf bank_mask:0xc
	v_mov_b32_dpp v129, v125 row_ror:8 row_mask:0xf bank_mask:0xc
	v_mov_b32_dpp v122, v224 quad_perm:[0,1,2,3] row_mask:0xf bank_mask:0x3
	v_mov_b32_dpp v123, v225 quad_perm:[0,1,2,3] row_mask:0xf bank_mask:0x3
	v_mov_b32_dpp v124, v228 quad_perm:[0,1,2,3] row_mask:0xf bank_mask:0x3
	v_mov_b32_dpp v125, v229 quad_perm:[0,1,2,3] row_mask:0xf bank_mask:0x3
	v_mov_b32_dpp v224, v118 row_ror:8 row_mask:0xf bank_mask:0x3
	v_mov_b32_dpp v225, v119 row_ror:8 row_mask:0xf bank_mask:0x3
	v_mov_b32_dpp v228, v120 row_ror:8 row_mask:0xf bank_mask:0x3
	v_mov_b32_dpp v229, v121 row_ror:8 row_mask:0xf bank_mask:0x3
	v_mov_b32_dpp v118, v106 row_ror:8 row_mask:0xf bank_mask:0xc
	v_mov_b32_dpp v119, v107 row_ror:8 row_mask:0xf bank_mask:0xc
	v_mov_b32_dpp v120, v108 row_ror:8 row_mask:0xf bank_mask:0xc
	v_mov_b32_dpp v121, v109 row_ror:8 row_mask:0xf bank_mask:0xc
	v_mov_b32_dpp v106, v224 quad_perm:[0,1,2,3] row_mask:0xf bank_mask:0x3
	v_mov_b32_dpp v107, v225 quad_perm:[0,1,2,3] row_mask:0xf bank_mask:0x3
	v_mov_b32_dpp v108, v228 quad_perm:[0,1,2,3] row_mask:0xf bank_mask:0x3
	v_mov_b32_dpp v109, v229 quad_perm:[0,1,2,3] row_mask:0xf bank_mask:0x3
	v_mov_b32_dpp v224, v114 row_ror:8 row_mask:0xf bank_mask:0x3
	v_mov_b32_dpp v225, v115 row_ror:8 row_mask:0xf bank_mask:0x3
	v_mov_b32_dpp v228, v116 row_ror:8 row_mask:0xf bank_mask:0x3
	v_mov_b32_dpp v229, v117 row_ror:8 row_mask:0xf bank_mask:0x3
	v_mov_b32_dpp v114, v110 row_ror:8 row_mask:0xf bank_mask:0xc
	v_mov_b32_dpp v115, v111 row_ror:8 row_mask:0xf bank_mask:0xc
	v_mov_b32_dpp v116, v112 row_ror:8 row_mask:0xf bank_mask:0xc
	v_mov_b32_dpp v117, v113 row_ror:8 row_mask:0xf bank_mask:0xc
	v_mov_b32_dpp v110, v224 quad_perm:[0,1,2,3] row_mask:0xf bank_mask:0x3
	v_mov_b32_dpp v111, v225 quad_perm:[0,1,2,3] row_mask:0xf bank_mask:0x3
	v_mov_b32_dpp v112, v228 quad_perm:[0,1,2,3] row_mask:0xf bank_mask:0x3
	v_mov_b32_dpp v113, v229 quad_perm:[0,1,2,3] row_mask:0xf bank_mask:0x3
	v_mov_b32_dpp v224, v102 row_ror:8 row_mask:0xf bank_mask:0x3
	v_mov_b32_dpp v225, v103 row_ror:8 row_mask:0xf bank_mask:0x3
	v_mov_b32_dpp v228, v104 row_ror:8 row_mask:0xf bank_mask:0x3
	v_mov_b32_dpp v229, v105 row_ror:8 row_mask:0xf bank_mask:0x3
	v_mov_b32_dpp v102, v90 row_ror:8 row_mask:0xf bank_mask:0xc
	v_mov_b32_dpp v103, v91 row_ror:8 row_mask:0xf bank_mask:0xc
	v_mov_b32_dpp v104, v92 row_ror:8 row_mask:0xf bank_mask:0xc
	v_mov_b32_dpp v105, v93 row_ror:8 row_mask:0xf bank_mask:0xc
	v_mov_b32_dpp v90, v224 quad_perm:[0,1,2,3] row_mask:0xf bank_mask:0x3
	v_mov_b32_dpp v91, v225 quad_perm:[0,1,2,3] row_mask:0xf bank_mask:0x3
	v_mov_b32_dpp v92, v228 quad_perm:[0,1,2,3] row_mask:0xf bank_mask:0x3
	v_mov_b32_dpp v93, v229 quad_perm:[0,1,2,3] row_mask:0xf bank_mask:0x3
	v_mov_b32_dpp v224, v98 row_ror:8 row_mask:0xf bank_mask:0x3
	v_mov_b32_dpp v225, v99 row_ror:8 row_mask:0xf bank_mask:0x3
	v_mov_b32_dpp v228, v100 row_ror:8 row_mask:0xf bank_mask:0x3
	v_mov_b32_dpp v229, v101 row_ror:8 row_mask:0xf bank_mask:0x3
	v_mov_b32_dpp v98, v94 row_ror:8 row_mask:0xf bank_mask:0xc
	v_mov_b32_dpp v99, v95 row_ror:8 row_mask:0xf bank_mask:0xc
	v_mov_b32_dpp v100, v96 row_ror:8 row_mask:0xf bank_mask:0xc
	v_mov_b32_dpp v101, v97 row_ror:8 row_mask:0xf bank_mask:0xc
	v_mov_b32_dpp v94, v224 quad_perm:[0,1,2,3] row_mask:0xf bank_mask:0x3
;     __device__ __forceinline__ void operator()(const f32x4 (&acc)[2][2][4][2], const pg8::Unit& u, int wr, int wc, int fr, int fq) const {
;     ...
;         const int col0 = u.pn * 256 + wc * 32 + 4 * fq;
;         const float* gp = gate + (size_t)bidx * 6144 + col0;
;         f32x4 gv[2][2];
; #pragma unroll
;         for (int bj = 0; bj < 2; ++bj)
; #pragma unroll
;             for (int n = 0; n < 2; ++n) gv[bj][n] = *(const f32x4*)(gp + bj * 128 + n * 16);
; #pragma unroll
;         for (int ai = 0; ai < 2; ++ai)
; #pragma unroll
;             for (int m = 0; m < 4; ++m) { const size_t ro = (size_t)(wr * 64 + fr + ai * 128 + m * 16) * DM + col0;
; #pragma unroll
;                 for (int bj = 0; bj < 2; ++bj)
; #pragma unroll
;                     for (int n = 0; n < 2; ++n) { const size_t o = ro + bj * 128 + n * 16; *(f32x4*)(outp + o) = *(const f32x4*)(inp + o) + gv[bj][n] * acc[ai][bj][m][n]; } }
	v_mov_b32_dpp v95, v225 quad_perm:[0,1,2,3] row_mask:0xf bank_mask:0x3
	v_mov_b32_dpp v96, v228 quad_perm:[0,1,2,3] row_mask:0xf bank_mask:0x3
	v_mov_b32_dpp v97, v229 quad_perm:[0,1,2,3] row_mask:0xf bank_mask:0x3
	v_mov_b32_dpp v224, v86 row_ror:8 row_mask:0xf bank_mask:0x3
	v_mov_b32_dpp v225, v87 row_ror:8 row_mask:0xf bank_mask:0x3
	v_mov_b32_dpp v228, v88 row_ror:8 row_mask:0xf bank_mask:0x3
	v_mov_b32_dpp v229, v89 row_ror:8 row_mask:0xf bank_mask:0x3
	v_mov_b32_dpp v86, v74 row_ror:8 row_mask:0xf bank_mask:0xc
	v_mov_b32_dpp v87, v75 row_ror:8 row_mask:0xf bank_mask:0xc
	v_mov_b32_dpp v88, v76 row_ror:8 row_mask:0xf bank_mask:0xc
	v_mov_b32_dpp v89, v77 row_ror:8 row_mask:0xf bank_mask:0xc
	v_mov_b32_dpp v74, v224 quad_perm:[0,1,2,3] row_mask:0xf bank_mask:0x3
	v_mov_b32_dpp v75, v225 quad_perm:[0,1,2,3] row_mask:0xf bank_mask:0x3
	v_mov_b32_dpp v76, v228 quad_perm:[0,1,2,3] row_mask:0xf bank_mask:0x3
	v_mov_b32_dpp v77, v229 quad_perm:[0,1,2,3] row_mask:0xf bank_mask:0x3
	v_mov_b32_dpp v224, v82 row_ror:8 row_mask:0xf bank_mask:0x3
	v_mov_b32_dpp v225, v83 row_ror:8 row_mask:0xf bank_mask:0x3
	v_mov_b32_dpp v228, v84 row_ror:8 row_mask:0xf bank_mask:0x3
	v_mov_b32_dpp v229, v85 row_ror:8 row_mask:0xf bank_mask:0x3
	v_mov_b32_dpp v82, v78 row_ror:8 row_mask:0xf bank_mask:0xc
	v_mov_b32_dpp v83, v79 row_ror:8 row_mask:0xf bank_mask:0xc
	v_mov_b32_dpp v84, v80 row_ror:8 row_mask:0xf bank_mask:0xc
	v_mov_b32_dpp v85, v81 row_ror:8 row_mask:0xf bank_mask:0xc
	v_mov_b32_dpp v78, v224 quad_perm:[0,1,2,3] row_mask:0xf bank_mask:0x3
	v_mov_b32_dpp v79, v225 quad_perm:[0,1,2,3] row_mask:0xf bank_mask:0x3
	v_mov_b32_dpp v80, v228 quad_perm:[0,1,2,3] row_mask:0xf bank_mask:0x3
	v_mov_b32_dpp v81, v229 quad_perm:[0,1,2,3] row_mask:0xf bank_mask:0x3
	v_mov_b32_dpp v224, v70 row_ror:8 row_mask:0xf bank_mask:0x3
	v_mov_b32_dpp v225, v71 row_ror:8 row_mask:0xf bank_mask:0x3
	v_mov_b32_dpp v228, v72 row_ror:8 row_mask:0xf bank_mask:0x3
	v_mov_b32_dpp v229, v73 row_ror:8 row_mask:0xf bank_mask:0x3
	v_mov_b32_dpp v70, v66 row_ror:8 row_mask:0xf bank_mask:0xc
	v_mov_b32_dpp v71, v67 row_ror:8 row_mask:0xf bank_mask:0xc
	v_mov_b32_dpp v72, v68 row_ror:8 row_mask:0xf bank_mask:0xc
	v_mov_b32_dpp v73, v69 row_ror:8 row_mask:0xf bank_mask:0xc
	v_mov_b32_dpp v66, v224 quad_perm:[0,1,2,3] row_mask:0xf bank_mask:0x3
	v_mov_b32_dpp v67, v225 quad_perm:[0,1,2,3] row_mask:0xf bank_mask:0x3
	v_mov_b32_dpp v68, v228 quad_perm:[0,1,2,3] row_mask:0xf bank_mask:0x3
	v_mov_b32_dpp v69, v229 quad_perm:[0,1,2,3] row_mask:0xf bank_mask:0x3
	v_mov_b32_dpp v224, v62 row_ror:8 row_mask:0xf bank_mask:0x3
	v_mov_b32_dpp v225, v63 row_ror:8 row_mask:0xf bank_mask:0x3
	v_mov_b32_dpp v228, v64 row_ror:8 row_mask:0xf bank_mask:0x3
	v_mov_b32_dpp v229, v65 row_ror:8 row_mask:0xf bank_mask:0x3
	v_mov_b32_dpp v62, v58 row_ror:8 row_mask:0xf bank_mask:0xc
	v_mov_b32_dpp v63, v59 row_ror:8 row_mask:0xf bank_mask:0xc
	v_mov_b32_dpp v64, v60 row_ror:8 row_mask:0xf bank_mask:0xc
	v_mov_b32_dpp v65, v61 row_ror:8 row_mask:0xf bank_mask:0xc
	v_mov_b32_dpp v58, v224 quad_perm:[0,1,2,3] row_mask:0xf bank_mask:0x3
	v_mov_b32_dpp v59, v225 quad_perm:[0,1,2,3] row_mask:0xf bank_mask:0x3
	v_mov_b32_dpp v60, v228 quad_perm:[0,1,2,3] row_mask:0xf bank_mask:0x3
	v_mov_b32_dpp v61, v229 quad_perm:[0,1,2,3] row_mask:0xf bank_mask:0x3
	v_mov_b32_dpp v224, v54 row_ror:8 row_mask:0xf bank_mask:0x3
	v_mov_b32_dpp v225, v55 row_ror:8 row_mask:0xf bank_mask:0x3
	v_mov_b32_dpp v228, v56 row_ror:8 row_mask:0xf bank_mask:0x3
	v_mov_b32_dpp v229, v57 row_ror:8 row_mask:0xf bank_mask:0x3
	v_mov_b32_dpp v54, v40 row_ror:8 row_mask:0xf bank_mask:0xc
	v_mov_b32_dpp v55, v41 row_ror:8 row_mask:0xf bank_mask:0xc
	v_mov_b32_dpp v56, v42 row_ror:8 row_mask:0xf bank_mask:0xc
	v_mov_b32_dpp v57, v43 row_ror:8 row_mask:0xf bank_mask:0xc
	v_mov_b32_dpp v40, v224 quad_perm:[0,1,2,3] row_mask:0xf bank_mask:0x3
	v_mov_b32_dpp v41, v225 quad_perm:[0,1,2,3] row_mask:0xf bank_mask:0x3
	v_mov_b32_dpp v42, v228 quad_perm:[0,1,2,3] row_mask:0xf bank_mask:0x3
	v_mov_b32_dpp v43, v229 quad_perm:[0,1,2,3] row_mask:0xf bank_mask:0x3
	v_mov_b32_dpp v224, v50 row_ror:8 row_mask:0xf bank_mask:0x3
	v_mov_b32_dpp v225, v51 row_ror:8 row_mask:0xf bank_mask:0x3
	v_mov_b32_dpp v228, v52 row_ror:8 row_mask:0xf bank_mask:0x3
	v_mov_b32_dpp v229, v53 row_ror:8 row_mask:0xf bank_mask:0x3
	v_mov_b32_dpp v50, v44 row_ror:8 row_mask:0xf bank_mask:0xc
	v_mov_b32_dpp v51, v45 row_ror:8 row_mask:0xf bank_mask:0xc
	v_mov_b32_dpp v52, v46 row_ror:8 row_mask:0xf bank_mask:0xc
	v_mov_b32_dpp v53, v47 row_ror:8 row_mask:0xf bank_mask:0xc
	v_mov_b32_dpp v44, v224 quad_perm:[0,1,2,3] row_mask:0xf bank_mask:0x3
	v_mov_b32_dpp v45, v225 quad_perm:[0,1,2,3] row_mask:0xf bank_mask:0x3
	v_mov_b32_dpp v46, v228 quad_perm:[0,1,2,3] row_mask:0xf bank_mask:0x3
	v_mov_b32_dpp v47, v229 quad_perm:[0,1,2,3] row_mask:0xf bank_mask:0x3
	v_mov_b32_dpp v224, v36 row_ror:8 row_mask:0xf bank_mask:0x3
	v_mov_b32_dpp v225, v37 row_ror:8 row_mask:0xf bank_mask:0x3
	v_mov_b32_dpp v228, v38 row_ror:8 row_mask:0xf bank_mask:0x3
	v_mov_b32_dpp v229, v39 row_ror:8 row_mask:0xf bank_mask:0x3
	v_mov_b32_dpp v36, v24 row_ror:8 row_mask:0xf bank_mask:0xc
	v_mov_b32_dpp v37, v25 row_ror:8 row_mask:0xf bank_mask:0xc
	v_mov_b32_dpp v38, v26 row_ror:8 row_mask:0xf bank_mask:0xc
	v_mov_b32_dpp v39, v27 row_ror:8 row_mask:0xf bank_mask:0xc
	v_mov_b32_dpp v24, v224 quad_perm:[0,1,2,3] row_mask:0xf bank_mask:0x3
	v_mov_b32_dpp v25, v225 quad_perm:[0,1,2,3] row_mask:0xf bank_mask:0x3
	v_mov_b32_dpp v26, v228 quad_perm:[0,1,2,3] row_mask:0xf bank_mask:0x3
;     __device__ __forceinline__ void operator()(const f32x4 (&acc)[2][2][4][2], const pg8::Unit& u, int wr, int wc, int fr, int fq) const {
;     ...
;         for (int ai = 0; ai < 2; ++ai)
; #pragma unroll
;             for (int m = 0; m < 4; ++m) { const size_t ro = (size_t)(wr * 64 + fr + ai * 128 + m * 16) * DM + col0;
; #pragma unroll
;                 for (int bj = 0; bj < 2; ++bj)
; #pragma unroll
;                     for (int n = 0; n < 2; ++n) { const size_t o = ro + bj * 128 + n * 16; *(f32x4*)(outp + o) = *(const f32x4*)(inp + o) + gv[bj][n] * acc[ai][bj][m][n]; } }
	v_mov_b32_dpp v27, v229 quad_perm:[0,1,2,3] row_mask:0xf bank_mask:0x3
	v_mov_b32_dpp v224, v32 row_ror:8 row_mask:0xf bank_mask:0x3
	v_mov_b32_dpp v225, v33 row_ror:8 row_mask:0xf bank_mask:0x3
	v_mov_b32_dpp v228, v34 row_ror:8 row_mask:0xf bank_mask:0x3
	v_mov_b32_dpp v229, v35 row_ror:8 row_mask:0xf bank_mask:0x3
	v_mov_b32_dpp v32, v28 row_ror:8 row_mask:0xf bank_mask:0xc
	v_mov_b32_dpp v33, v29 row_ror:8 row_mask:0xf bank_mask:0xc
	v_mov_b32_dpp v34, v30 row_ror:8 row_mask:0xf bank_mask:0xc
	v_mov_b32_dpp v35, v31 row_ror:8 row_mask:0xf bank_mask:0xc
	v_mov_b32_dpp v28, v224 quad_perm:[0,1,2,3] row_mask:0xf bank_mask:0x3
	v_mov_b32_dpp v29, v225 quad_perm:[0,1,2,3] row_mask:0xf bank_mask:0x3
	v_mov_b32_dpp v30, v228 quad_perm:[0,1,2,3] row_mask:0xf bank_mask:0x3
	v_mov_b32_dpp v31, v229 quad_perm:[0,1,2,3] row_mask:0xf bank_mask:0x3
	v_mov_b32_dpp v224, v20 row_ror:8 row_mask:0xf bank_mask:0x3
	v_mov_b32_dpp v225, v21 row_ror:8 row_mask:0xf bank_mask:0x3
	v_mov_b32_dpp v228, v22 row_ror:8 row_mask:0xf bank_mask:0x3
	v_mov_b32_dpp v229, v23 row_ror:8 row_mask:0xf bank_mask:0x3
	v_mov_b32_dpp v20, v8 row_ror:8 row_mask:0xf bank_mask:0xc
	v_mov_b32_dpp v21, v9 row_ror:8 row_mask:0xf bank_mask:0xc
	v_mov_b32_dpp v22, v10 row_ror:8 row_mask:0xf bank_mask:0xc
	v_mov_b32_dpp v23, v11 row_ror:8 row_mask:0xf bank_mask:0xc
	v_mov_b32_dpp v8, v224 quad_perm:[0,1,2,3] row_mask:0xf bank_mask:0x3
	v_mov_b32_dpp v9, v225 quad_perm:[0,1,2,3] row_mask:0xf bank_mask:0x3
	v_mov_b32_dpp v10, v228 quad_perm:[0,1,2,3] row_mask:0xf bank_mask:0x3
	v_mov_b32_dpp v11, v229 quad_perm:[0,1,2,3] row_mask:0xf bank_mask:0x3
	v_mov_b32_dpp v224, v16 row_ror:8 row_mask:0xf bank_mask:0x3
	v_mov_b32_dpp v225, v17 row_ror:8 row_mask:0xf bank_mask:0x3
	v_mov_b32_dpp v228, v18 row_ror:8 row_mask:0xf bank_mask:0x3
	v_mov_b32_dpp v229, v19 row_ror:8 row_mask:0xf bank_mask:0x3
	v_mov_b32_dpp v16, v12 row_ror:8 row_mask:0xf bank_mask:0xc
	v_mov_b32_dpp v17, v13 row_ror:8 row_mask:0xf bank_mask:0xc
	v_mov_b32_dpp v18, v14 row_ror:8 row_mask:0xf bank_mask:0xc
	v_mov_b32_dpp v19, v15 row_ror:8 row_mask:0xf bank_mask:0xc
	v_mov_b32_dpp v12, v224 quad_perm:[0,1,2,3] row_mask:0xf bank_mask:0x3
	v_mov_b32_dpp v13, v225 quad_perm:[0,1,2,3] row_mask:0xf bank_mask:0x3
	v_mov_b32_dpp v14, v228 quad_perm:[0,1,2,3] row_mask:0xf bank_mask:0x3
	v_mov_b32_dpp v15, v229 quad_perm:[0,1,2,3] row_mask:0xf bank_mask:0x3
	v_mov_b32_dpp v224, v4 row_ror:8 row_mask:0xf bank_mask:0x3
	v_mov_b32_dpp v225, v5 row_ror:8 row_mask:0xf bank_mask:0x3
	v_mov_b32_dpp v228, v6 row_ror:8 row_mask:0xf bank_mask:0x3
	v_mov_b32_dpp v229, v7 row_ror:8 row_mask:0xf bank_mask:0x3
	v_mov_b32_dpp v4, v0 row_ror:8 row_mask:0xf bank_mask:0xc
	v_mov_b32_dpp v5, v1 row_ror:8 row_mask:0xf bank_mask:0xc
	v_mov_b32_dpp v6, v2 row_ror:8 row_mask:0xf bank_mask:0xc
	v_mov_b32_dpp v7, v3 row_ror:8 row_mask:0xf bank_mask:0xc
	v_mov_b32_dpp v0, v224 quad_perm:[0,1,2,3] row_mask:0xf bank_mask:0x3
	v_mov_b32_dpp v1, v225 quad_perm:[0,1,2,3] row_mask:0xf bank_mask:0x3
	v_mov_b32_dpp v2, v228 quad_perm:[0,1,2,3] row_mask:0xf bank_mask:0x3
	v_mov_b32_dpp v3, v229 quad_perm:[0,1,2,3] row_mask:0xf bank_mask:0x3
	s_waitcnt vmcnt(9)
	v_cndmask_b32_e64 v142, v138, v142, s[22:23]
	v_cndmask_b32_e64 v143, v139, v143, s[22:23]
	v_cndmask_b32_e64 v144, v140, v144, s[22:23]
	v_cndmask_b32_e64 v145, v141, v145, s[22:23]
	v_cndmask_b32_e64 v134, v130, v134, s[22:23]
	v_cndmask_b32_e64 v135, v131, v135, s[22:23]
	v_cndmask_b32_e64 v136, v132, v136, s[22:23]
	v_cndmask_b32_e64 v137, v133, v137, s[22:23]
	s_waitcnt vmcnt(8)
	v_pk_fma_f32 v[128:129], v[128:129], v[144:145], v[194:195]
	v_pk_fma_f32 v[126:127], v[126:127], v[142:143], v[192:193]
	global_load_dwordx4 v[192:195], v186, s[20:21]
	global_store_dwordx4 v176, v[126:129], s[16:17]
	s_waitcnt vmcnt(9)
	v_pk_fma_f32 v[124:125], v[124:125], v[144:145], v[198:199]
	v_pk_fma_f32 v[122:123], v[122:123], v[142:143], v[196:197]
	global_load_dwordx4 v[196:199], v178, s[20:21] offset:512
	global_store_dwordx4 v184, v[122:125], s[16:17]
	s_waitcnt vmcnt(10)
	v_pk_fma_f32 v[120:121], v[120:121], v[136:137], v[202:203]
	v_pk_fma_f32 v[118:119], v[118:119], v[134:135], v[200:201]
	global_load_dwordx4 v[200:203], v186, s[20:21] offset:512
	global_store_dwordx4 v176, v[118:121], s[16:17] offset:512
	s_waitcnt vmcnt(11)
	v_pk_fma_f32 v[108:109], v[108:109], v[136:137], v[206:207]
	v_pk_fma_f32 v[106:107], v[106:107], v[134:135], v[204:205]
	global_load_dwordx4 v[204:207], v179, s[20:21]
	global_store_dwordx4 v184, v[106:109], s[16:17] offset:512
	s_waitcnt vmcnt(12)
	v_pk_fma_f32 v[116:117], v[116:117], v[144:145], v[210:211]
	v_pk_fma_f32 v[114:115], v[114:115], v[142:143], v[208:209]
	global_load_dwordx4 v[208:211], v187, s[20:21]
	global_store_dwordx4 v177, v[114:117], s[16:17]
	s_waitcnt vmcnt(13)
	v_pk_fma_f32 v[112:113], v[112:113], v[144:145], v[214:215]
	v_pk_fma_f32 v[110:111], v[110:111], v[142:143], v[212:213]
	global_load_dwordx4 v[212:215], v179, s[20:21] offset:512
	global_store_dwordx4 v185, v[110:113], s[16:17]
	s_waitcnt vmcnt(14)
	v_pk_fma_f32 v[104:105], v[104:105], v[136:137], v[218:219]
	v_pk_fma_f32 v[102:103], v[102:103], v[134:135], v[216:217]
	global_load_dwordx4 v[216:219], v187, s[20:21] offset:512
	global_store_dwordx4 v177, v[102:105], s[16:17] offset:512
	s_waitcnt vmcnt(15)
	v_pk_fma_f32 v[92:93], v[92:93], v[136:137], v[236:237]
	v_pk_fma_f32 v[90:91], v[90:91], v[134:135], v[234:235]
	global_load_dwordx4 v[234:237], v180, s[20:21]
	global_store_dwordx4 v185, v[90:93], s[16:17] offset:512
	s_waitcnt vmcnt(16)
;     __device__ __forceinline__ void operator()(const f32x4 (&acc)[2][2][4][2], const pg8::Unit& u, int wr, int wc, int fr, int fq) const {
;     ...
;         for (int ai = 0; ai < 2; ++ai)
; #pragma unroll
;             for (int m = 0; m < 4; ++m) { const size_t ro = (size_t)(wr * 64 + fr + ai * 128 + m * 16) * DM + col0;
; #pragma unroll
;                 for (int bj = 0; bj < 2; ++bj)
; #pragma unroll
;                     for (int n = 0; n < 2; ++n) { const size_t o = ro + bj * 128 + n * 16; *(f32x4*)(outp + o) = *(const f32x4*)(inp + o) + gv[bj][n] * acc[ai][bj][m][n]; } }
	v_pk_fma_f32 v[100:101], v[100:101], v[144:145], v[240:241]
	v_pk_fma_f32 v[98:99], v[98:99], v[142:143], v[238:239]
	global_load_dwordx4 v[238:241], v188, s[20:21]
	global_store_dwordx4 v178, v[98:101], s[16:17]
	s_waitcnt vmcnt(17)
	v_pk_fma_f32 v[96:97], v[96:97], v[144:145], v[194:195]
	v_pk_fma_f32 v[94:95], v[94:95], v[142:143], v[192:193]
	global_load_dwordx4 v[192:195], v180, s[20:21] offset:512
	global_store_dwordx4 v186, v[94:97], s[16:17]
	s_waitcnt vmcnt(17)
	v_pk_fma_f32 v[88:89], v[88:89], v[136:137], v[198:199]
	v_pk_fma_f32 v[86:87], v[86:87], v[134:135], v[196:197]
	global_load_dwordx4 v[196:199], v188, s[20:21] offset:512
	global_store_dwordx4 v178, v[86:89], s[16:17] offset:512
	s_waitcnt vmcnt(17)
	v_pk_fma_f32 v[76:77], v[76:77], v[136:137], v[202:203]
	v_pk_fma_f32 v[74:75], v[74:75], v[134:135], v[200:201]
	global_load_dwordx4 v[200:203], v181, s[20:21]
	global_store_dwordx4 v186, v[74:77], s[16:17] offset:512
	s_waitcnt vmcnt(17)
	v_pk_fma_f32 v[84:85], v[84:85], v[144:145], v[206:207]
	v_pk_fma_f32 v[82:83], v[82:83], v[142:143], v[204:205]
	global_load_dwordx4 v[204:207], v189, s[20:21]
	global_store_dwordx4 v179, v[82:85], s[16:17]
	s_waitcnt vmcnt(17)
	v_pk_fma_f32 v[80:81], v[80:81], v[144:145], v[210:211]
	v_pk_fma_f32 v[78:79], v[78:79], v[142:143], v[208:209]
	global_load_dwordx4 v[208:211], v181, s[20:21] offset:512
	global_store_dwordx4 v187, v[78:81], s[16:17]
	s_waitcnt vmcnt(17)
	v_pk_fma_f32 v[72:73], v[72:73], v[136:137], v[214:215]
	v_pk_fma_f32 v[70:71], v[70:71], v[134:135], v[212:213]
	global_load_dwordx4 v[212:215], v189, s[20:21] offset:512
	global_store_dwordx4 v179, v[70:73], s[16:17] offset:512
	s_waitcnt vmcnt(17)
	v_pk_fma_f32 v[68:69], v[68:69], v[136:137], v[218:219]
	v_pk_fma_f32 v[66:67], v[66:67], v[134:135], v[216:217]
	global_load_dwordx4 v[216:219], v182, s[20:21]
	global_store_dwordx4 v187, v[66:69], s[16:17] offset:512
	s_waitcnt vmcnt(17)
	v_pk_fma_f32 v[64:65], v[64:65], v[144:145], v[236:237]
	v_pk_fma_f32 v[62:63], v[62:63], v[142:143], v[234:235]
	global_load_dwordx4 v[234:237], v190, s[20:21]
	global_store_dwordx4 v180, v[62:65], s[16:17]
	s_waitcnt vmcnt(17)
	v_pk_fma_f32 v[60:61], v[60:61], v[144:145], v[240:241]
	v_pk_fma_f32 v[58:59], v[58:59], v[142:143], v[238:239]
	global_load_dwordx4 v[238:241], v182, s[20:21] offset:512
	global_store_dwordx4 v188, v[58:61], s[16:17]
	s_waitcnt vmcnt(17)
	v_pk_fma_f32 v[56:57], v[56:57], v[136:137], v[194:195]
	v_pk_fma_f32 v[54:55], v[54:55], v[134:135], v[192:193]
	global_load_dwordx4 v[192:195], v190, s[20:21] offset:512
	global_store_dwordx4 v180, v[54:57], s[16:17] offset:512
	s_waitcnt vmcnt(17)
	v_pk_fma_f32 v[42:43], v[42:43], v[136:137], v[198:199]
	v_pk_fma_f32 v[40:41], v[40:41], v[134:135], v[196:197]
	global_load_dwordx4 v[196:199], v183, s[20:21]
	global_store_dwordx4 v188, v[40:43], s[16:17] offset:512
	s_waitcnt vmcnt(17)
	v_pk_fma_f32 v[52:53], v[52:53], v[144:145], v[202:203]
	v_pk_fma_f32 v[50:51], v[50:51], v[142:143], v[200:201]
	global_load_dwordx4 v[200:203], v191, s[20:21]
	global_store_dwordx4 v181, v[50:53], s[16:17]
	s_waitcnt vmcnt(17)
	v_pk_fma_f32 v[46:47], v[46:47], v[144:145], v[206:207]
	v_pk_fma_f32 v[44:45], v[44:45], v[142:143], v[204:205]
	global_load_dwordx4 v[204:207], v183, s[20:21] offset:512
	global_store_dwordx4 v189, v[44:47], s[16:17]
	s_waitcnt vmcnt(17)
	v_pk_fma_f32 v[38:39], v[38:39], v[136:137], v[210:211]
	v_pk_fma_f32 v[36:37], v[36:37], v[134:135], v[208:209]
	global_load_dwordx4 v[208:211], v191, s[20:21] offset:512
	s_mov_b64 s[20:21], s[12:13]
	global_store_dwordx4 v181, v[36:39], s[16:17] offset:512
	s_waitcnt vmcnt(17)
	v_pk_fma_f32 v[26:27], v[26:27], v[136:137], v[214:215]
	v_pk_fma_f32 v[24:25], v[24:25], v[134:135], v[212:213]
	global_store_dwordx4 v189, v[24:27], s[16:17] offset:512
	s_waitcnt vmcnt(16)
	v_pk_fma_f32 v[34:35], v[34:35], v[144:145], v[218:219]
	v_pk_fma_f32 v[32:33], v[32:33], v[142:143], v[216:217]
	global_store_dwordx4 v182, v[32:35], s[16:17]
	s_waitcnt vmcnt(15)
	v_pk_fma_f32 v[30:31], v[30:31], v[144:145], v[236:237]
	v_pk_fma_f32 v[28:29], v[28:29], v[142:143], v[234:235]
	global_store_dwordx4 v190, v[28:31], s[16:17]
	s_waitcnt vmcnt(14)
	v_pk_fma_f32 v[22:23], v[22:23], v[136:137], v[240:241]
	v_pk_fma_f32 v[20:21], v[20:21], v[134:135], v[238:239]
	global_store_dwordx4 v182, v[20:23], s[16:17] offset:512
	s_waitcnt vmcnt(13)
	v_pk_fma_f32 v[10:11], v[10:11], v[136:137], v[194:195]
	v_pk_fma_f32 v[8:9], v[8:9], v[134:135], v[192:193]
	global_store_dwordx4 v190, v[8:11], s[16:17] offset:512
	s_waitcnt vmcnt(12)
	v_pk_fma_f32 v[18:19], v[18:19], v[144:145], v[198:199]
	v_pk_fma_f32 v[16:17], v[16:17], v[142:143], v[196:197]
	global_store_dwordx4 v183, v[16:19], s[16:17]
	s_waitcnt vmcnt(11)
	v_pk_fma_f32 v[14:15], v[14:15], v[144:145], v[202:203]
	v_pk_fma_f32 v[12:13], v[12:13], v[142:143], v[200:201]
	global_store_dwordx4 v191, v[12:15], s[16:17]
	s_waitcnt vmcnt(10)
	v_pk_fma_f32 v[6:7], v[6:7], v[136:137], v[206:207]
	v_pk_fma_f32 v[4:5], v[4:5], v[134:135], v[204:205]
	global_store_dwordx4 v183, v[4:7], s[16:17] offset:512
	s_waitcnt vmcnt(9)
	v_pk_fma_f32 v[2:3], v[2:3], v[136:137], v[210:211]
	v_pk_fma_f32 v[0:1], v[0:1], v[134:135], v[208:209]
	global_store_dwordx4 v191, v[0:3], s[16:17] offset:512
	s_mov_b64 s[16:17], s[2:3]
	s_and_b64 vcc, exec, s[40:41]
	s_cbranch_vccnz .LBB0_273
